# GEMM K-loop: per-phase setprio flips deleted, one static setprio 1 for waves 0-3 at job entry, reset at job end
# speedup vs baseline: 1.0075x; 1.0075x over previous
; __global__ void __launch_bounds__(512) mega(P p_unused) {
;     ...
;         for (int j = 0; j < nj; ++j) { const pg8::Job jb = get_job(kp, ph, l, j); run_job(smem, jb); }
.LBB0_480:
	s_setprio 0
	s_add_i32 s24, s24, 1
	s_cmp_eq_u32 s24, s65
	s_cbranch_scc1 .LBB0_1101

; #define PG8_STAGE(bufoff, gbase, voff) do { _Pragma("unroll") for (int _i = 0; _i < 2; ++_i) \
;     __builtin_amdgcn_global_load_lds((const unsigned*)((const char*)(gbase) + (voff)[_i]), (PG8_LAS unsigned*)(lds + (bufoff) + ldsw + _i * 8192), 16, 0, 0); } while (0)
; #define PG8_BAR __builtin_amdgcn_s_barrier()
; template <class Epi>
; DEV void gemm_phase(PG8_LAS unsigned char* lds, const Gemm g, const StaticOrder& S, const Epi& E) {
;     ...
;   const char* cA = (const char*)g.A + (size_t)cur.pm * tstepA + (size_t)cur.pn * pnA; const char* cB = (const char*)g.Bt + (size_t)cur.pn * tstepB;
;   PG8_STAGE(PG8_SB(0, 0), cB, voffB); PG8_STAGE(PG8_SB(0, 1), cB + hstepB, voffB); PG8_STAGE(PG8_SA(0, 0), cA, voffA); PG8_STAGE(PG8_SA(0, 1), cA + hstepA, voffA);
;   if (wr == 1) PG8_BAR;
.LBB0_539:
	s_xor_b64 s[2:3], s[18:19], -1
	v_writelane_b32 v255, s2, 23
	s_xor_b64 s[14:15], s[16:17], -1
	s_xor_b64 s[20:21], s[8:9], -1
	v_writelane_b32 v255, s3, 24
	v_ashrrev_i32_e32 v5, 6, v5
	v_readlane_b32 s2, v255, 15
	v_readlane_b32 s3, v255, 16
	s_xor_b64 s[18:19], s[2:3], -1
	v_ashrrev_i32_e32 v7, 6, v9
	s_and_b64 vcc, exec, s[0:1]
	s_cbranch_vccz .LBB0_480
	v_lshlrev_b32_e32 v3, 3, v3
	v_lshlrev_b32_e32 v1, 3, v1
	v_and_b32_e32 v3, -16, v3
	v_and_b32_e32 v1, -16, v1
	v_add_u32_e32 v3, v7, v3
	v_and_b32_e32 v7, 3, v7
	s_mov_b32 s3, 0x7fffffe0
	v_add_u32_e32 v1, v5, v1
	v_and_b32_e32 v5, 3, v5
	v_and_or_b32 v7, v3, s3, v7
	s_lshl_b64 s[26:27], s[36:37], 9
	v_and_or_b32 v5, v1, s3, v5
	s_ashr_i32 s3, s31, 31
	s_mul_i32 s3, s26, s3
	s_mul_hi_u32 s7, s26, s31
	s_lshr_b64 s[8:9], s[36:37], 23
	s_add_i32 s3, s7, s3
	s_mul_i32 s7, s8, s31
	s_add_i32 s7, s3, s7
	s_ashr_i32 s3, s72, 31
	s_mul_hi_u32 s9, s82, s72
	s_mul_i32 s11, s82, s3
	s_lshl_b64 s[28:29], s[84:85], 9
	s_add_i32 s9, s9, s11
	s_mul_i32 s11, s83, s72
	v_lshlrev_b32_e32 v9, 1, v3
	v_lshrrev_b32_e32 v10, 2, v3
	s_add_i32 s11, s9, s11
	s_mul_i32 s3, s28, s3
	s_mul_hi_u32 s9, s28, s72
	v_and_b32_e32 v9, 24, v9
	v_and_b32_e32 v10, 4, v10
	s_add_i32 s3, s9, s3
	s_lshr_b32 s9, s84, 23
	v_or3_b32 v7, v7, v10, v9
	v_mul_lo_u32 v3, s36, v3
	s_ashr_i32 s1, s6, 6
	s_mul_i32 s9, s9, s72
	v_writelane_b32 v255, s24, 25
	v_add_lshl_u32 v178, v6, v3, 1
	v_mul_lo_u32 v3, v7, s84
	s_ashr_i32 s0, s6, 8
	s_lshl_b64 s[22:23], s[36:37], 8
	s_lshl_b64 s[24:25], s[84:85], 8
	s_lshl_b32 s2, s1, 10
	s_add_i32 s3, s3, s9
	s_mul_i32 s9, s28, s72
	v_add_lshl_u32 v180, v3, v4, 1
	v_lshlrev_b32_e32 v3, 1, v1
	v_lshrrev_b32_e32 v4, 2, v1
	s_add_u32 s48, s58, s9
	v_and_b32_e32 v3, 24, v3
	v_and_b32_e32 v4, 4, v4
	s_mul_i32 s8, s26, s31
	s_addc_u32 s49, s59, s3
	s_add_i32 s3, s2, 0x10000
	s_add_i32 s74, s2, 0x12000
	v_or3_b32 v3, v5, v4, v3
	v_mul_lo_u32 v1, s36, v1
	s_add_u32 s17, s60, s8
	v_add_lshl_u32 v182, v2, v1, 1
	v_mul_lo_u32 v1, v3, s84
	s_addc_u32 s7, s61, s7
	v_add_lshl_u32 v184, v1, v0, 1
	s_mov_b32 m0, s3
	s_add_u32 s8, s48, s24
	s_mul_i32 s16, s82, s72
	s_mov_b64 s[40:41], s[84:85]
	global_load_lds_dwordx4 v184, s[48:49]
	s_mov_b32 m0, s74
	s_addc_u32 s9, s49, s25
	s_add_i32 s75, s2, 0x14000
	s_add_i32 s84, s2, 0x16000
	global_load_lds_dwordx4 v180, s[48:49]
	s_mov_b32 m0, s75
	s_add_u32 s44, s17, s16
	v_mov_b32_e32 v185, v41
	v_mov_b32_e32 v181, v41
	global_load_lds_dwordx4 v184, s[8:9]
	s_mov_b32 m0, s84
	s_addc_u32 s45, s7, s11
	s_add_i32 s85, s2, 0x2000
	v_lshl_add_u64 v[4:5], s[8:9], 0, v[184:185]
	v_lshl_add_u64 v[6:7], s[8:9], 0, v[180:181]
	global_load_lds_dwordx4 v180, s[8:9]
	s_mov_b32 m0, s2
	s_add_u32 s8, s44, s22
	global_load_lds_dwordx4 v182, s[44:45]
	s_mov_b32 m0, s85
	s_addc_u32 s9, s45, s23
	s_add_i32 s33, s2, 0x4000
	global_load_lds_dwordx4 v178, s[44:45]
	s_mov_b32 m0, s33
	s_add_i32 s30, s2, 0x6000
	global_load_lds_dwordx4 v182, s[8:9]
	s_mov_b32 m0, s30
	s_cmp_eq_u32 s0, 1
	global_load_lds_dwordx4 v178, s[8:9]
	s_cselect_b64 s[8:9], -1, 0
	v_writelane_b32 v255, s8, 26
	v_lshl_add_u64 v[0:1], s[48:49], 0, v[184:185]
	v_lshl_add_u64 v[2:3], s[48:49], 0, v[180:181]
	v_writelane_b32 v255, s9, 27
	s_setprio 1
	s_cmp_lg_u32 s0, 1
	s_cbranch_scc1 .LBB0_542
	s_setprio 0
	s_barrier

; #define PG8_STAGE(bufoff, gbase, voff) do { _Pragma("unroll") for (int _i = 0; _i < 2; ++_i) \
;     __builtin_amdgcn_global_load_lds((const unsigned*)((const char*)(gbase) + (voff)[_i]), (PG8_LAS unsigned*)(lds + (bufoff) + ldsw + _i * 8192), 16, 0, 0); } while (0)
; #define PG8_LDA(dst, b, h) do { _Pragma("unroll") for (int m = 0; m < 4; ++m) _Pragma("unroll") for (int k = 0; k < 2; ++k) dst[m][k] = *(const PG8_LAS bf16x8*)(lds + PG8_SA(b, h) + aoff + m * 2048 + k * 1024); } while (0)
; #define PG8_LDB(dst, b, h) do { _Pragma("unroll") for (int n = 0; n < 2; ++n) _Pragma("unroll") for (int k = 0; k < 2; ++k) dst[n][k] = *(const PG8_LAS bf16x8*)(lds + PG8_SB(b, h) + boff + n * 2048 + k * 1024); } while (0)
; #define PG8_MMA(ai, bj, At, Bt) do { __builtin_amdgcn_s_setprio(1); _Pragma("unroll") for (int m = 0; m < 4; ++m) _Pragma("unroll") for (int n = 0; n < 2; ++n) _Pragma("unroll") for (int k = 0; k < 2; ++k) \
;     acc[ai][bj][m][n] = __builtin_amdgcn_mfma_f32_16x16x32_bf16(Bt[n][k], At[m][k], acc[ai][bj][m][n], 0, 0, 0); __builtin_amdgcn_s_setprio(0); } while (0)
; #define PG8_WAIT_V(n) asm volatile("s_waitcnt vmcnt(" #n ")" ::: "memory")
; #define PG8_WAIT_L(n) asm volatile("s_waitcnt lgkmcnt(" #n ")" ::: "memory")
; #define PG8_BAR __builtin_amdgcn_s_barrier()
; #define PG8_SCHED __builtin_amdgcn_sched_barrier(0)
; template <class Epi>
; DEV void gemm_phase(PG8_LAS unsigned char* lds, const Gemm g, const StaticOrder& S, const Epi& E) {
;     ...
;       PG8_LDB(B0, 0, 0); PG8_LDB(B1, 0, 1); PG8_SCHED; PG8_LDA(At, 0, 0); PG8_STAGE(PG8_SA(1, 1), a1 + hstepA, voffA);
;       PG8_WAIT_V(8); PG8_WAIT_L(0); PG8_BAR; PG8_MMA(0, 0, At, B0); PG8_MMA(0, 1, At, B1); PG8_BAR; PG8_SCHED;
;       PG8_LDA(At, 0, 1); PG8_STAGE(PG8_SB(0, 0), b2, voffB); PG8_STAGE(PG8_SB(0, 1), b2 + hstepB, voffB); PG8_STAGE(PG8_SA(0, 0), a2, voffA);
;       PG8_WAIT_V(8); PG8_WAIT_L(0); PG8_BAR; PG8_MMA(1, 0, At, B0); PG8_MMA(1, 1, At, B1); PG8_BAR; PG8_SCHED;
.LBB0_556:
	v_or_b32_e32 v40, 0x10000, v224
	v_add_u32_e32 v134, 0x10400, v224
	s_waitcnt lgkmcnt(0)
	ds_read_b128 v[130:133], v40
	ds_read_b128 v[134:137], v134
	v_add_u32_e32 v40, 0x10800, v224
	v_add_u32_e32 v142, 0x10c00, v224
	ds_read_b128 v[138:141], v40
	ds_read_b128 v[142:145], v142
	v_or_b32_e32 v40, 0x14000, v224
	v_add_u32_e32 v150, 0x14400, v224
	ds_read_b128 v[146:149], v40
	ds_read_b128 v[150:153], v150
	v_add_u32_e32 v40, 0x14800, v224
	v_add_u32_e32 v158, 0x14c00, v224
	ds_read_b128 v[154:157], v40
	ds_read_b128 v[158:161], v158
	s_add_i32 s50, s50, 2
	s_add_u32 s46, s42, s34
	s_addc_u32 s47, s43, s35
	s_and_b64 s[48:49], exec, s[48:49]
	s_cselect_b32 s49, s93, s11
	s_cselect_b32 s48, s92, s10
	v_lshl_add_u64 v[198:199], s[44:45], 0, v[190:191]
	s_add_i32 m0, s2, 0xc000
	ds_read_b128 v[162:165], v223
	ds_read_b128 v[166:169], v223 offset:1024
	ds_read_b128 v[170:173], v223 offset:2048
	ds_read_b128 v[174:177], v223 offset:3072
	ds_read_b128 v[194:197], v223 offset:4096
	ds_read_b128 v[202:205], v223 offset:5120
	ds_read_b128 v[206:209], v223 offset:6144
	ds_read_b128 v[210:213], v223 offset:7168
	global_load_lds_dwordx4 v[198:199], off
	v_lshl_add_u64 v[198:199], s[44:45], 0, v[192:193]
	s_mov_b32 m0, s5
	s_nop 0
	global_load_lds_dwordx4 v[198:199], off
	s_waitcnt vmcnt(8)
	s_waitcnt lgkmcnt(0)
	s_barrier
	s_waitcnt lgkmcnt(0)
	v_mfma_f32_16x16x32_bf16 v[126:129], v[130:133], v[162:165], v[126:129]
	v_mfma_f32_16x16x32_bf16 v[122:125], v[138:141], v[162:165], v[122:125]
	v_mfma_f32_16x16x32_bf16 v[118:121], v[130:133], v[170:173], v[118:121]
	v_mfma_f32_16x16x32_bf16 v[110:113], v[138:141], v[170:173], v[110:113]
	v_mfma_f32_16x16x32_bf16 v[94:97], v[130:133], v[194:197], v[94:97]
	v_mfma_f32_16x16x32_bf16 v[90:93], v[138:141], v[194:197], v[90:93]
	v_mfma_f32_16x16x32_bf16 v[86:89], v[130:133], v[206:209], v[86:89]
	v_mfma_f32_16x16x32_bf16 v[78:81], v[138:141], v[206:209], v[78:81]
	v_mfma_f32_16x16x32_bf16 v[126:129], v[134:137], v[166:169], v[126:129]
	v_mfma_f32_16x16x32_bf16 v[122:125], v[142:145], v[166:169], v[122:125]
	v_mfma_f32_16x16x32_bf16 v[118:121], v[134:137], v[174:177], v[118:121]
	v_mfma_f32_16x16x32_bf16 v[110:113], v[142:145], v[174:177], v[110:113]
	v_mfma_f32_16x16x32_bf16 v[94:97], v[134:137], v[202:205], v[94:97]
	v_mfma_f32_16x16x32_bf16 v[90:93], v[142:145], v[202:205], v[90:93]
	v_mfma_f32_16x16x32_bf16 v[86:89], v[134:137], v[210:213], v[86:89]
	v_mfma_f32_16x16x32_bf16 v[78:81], v[142:145], v[210:213], v[78:81]
	v_mfma_f32_16x16x32_bf16 v[114:117], v[146:149], v[162:165], v[114:117]
	v_mfma_f32_16x16x32_bf16 v[106:109], v[154:157], v[162:165], v[106:109]
	v_mfma_f32_16x16x32_bf16 v[102:105], v[146:149], v[170:173], v[102:105]
	v_mfma_f32_16x16x32_bf16 v[98:101], v[154:157], v[170:173], v[98:101]
	v_mfma_f32_16x16x32_bf16 v[82:85], v[146:149], v[194:197], v[82:85]
	v_mfma_f32_16x16x32_bf16 v[74:77], v[154:157], v[194:197], v[74:77]
	v_mfma_f32_16x16x32_bf16 v[70:73], v[146:149], v[206:209], v[70:73]
	v_mfma_f32_16x16x32_bf16 v[66:69], v[154:157], v[206:209], v[66:69]
	v_mfma_f32_16x16x32_bf16 v[114:117], v[150:153], v[166:169], v[114:117]
	v_mfma_f32_16x16x32_bf16 v[106:109], v[158:161], v[166:169], v[106:109]
	v_mfma_f32_16x16x32_bf16 v[102:105], v[150:153], v[174:177], v[102:105]
	v_mfma_f32_16x16x32_bf16 v[98:101], v[158:161], v[174:177], v[98:101]
	v_mfma_f32_16x16x32_bf16 v[82:85], v[150:153], v[202:205], v[82:85]
	v_mfma_f32_16x16x32_bf16 v[74:77], v[158:161], v[202:205], v[74:77]
	v_mfma_f32_16x16x32_bf16 v[70:73], v[150:153], v[210:213], v[70:73]
	v_mfma_f32_16x16x32_bf16 v[66:69], v[158:161], v[210:213], v[66:69]
	s_barrier
	s_mov_b32 m0, s3
	v_lshl_add_u64 v[198:199], s[48:49], 0, v[184:185]
	v_lshl_add_u64 v[214:215], s[48:49], 0, v[180:181]
	s_add_u32 s48, s48, s24
	ds_read_b128 v[162:165], v223 offset:16384
	ds_read_b128 v[166:169], v223 offset:17408
	ds_read_b128 v[170:173], v223 offset:18432
	ds_read_b128 v[174:177], v223 offset:19456
	ds_read_b128 v[194:197], v223 offset:20480
	ds_read_b128 v[202:205], v223 offset:21504
	ds_read_b128 v[206:209], v223 offset:22528
	ds_read_b128 v[210:213], v223 offset:23552
	global_load_lds_dwordx4 v[198:199], off
	s_mov_b32 m0, s74
	s_addc_u32 s49, s49, s25
	global_load_lds_dwordx4 v[214:215], off
	v_lshl_add_u64 v[216:217], s[48:49], 0, v[184:185]
	s_mov_b32 m0, s75
	v_lshl_add_u64 v[218:219], s[48:49], 0, v[180:181]
	global_load_lds_dwordx4 v[216:217], off
	s_mov_b32 m0, s84
	v_lshl_add_u64 v[220:221], s[42:43], 0, v[182:183]
	global_load_lds_dwordx4 v[218:219], off
	s_mov_b32 m0, s2
	s_nop 0
	global_load_lds_dwordx4 v[220:221], off
	v_lshl_add_u64 v[220:221], s[42:43], 0, v[178:179]
	s_mov_b32 m0, s85
	s_nop 0
	global_load_lds_dwordx4 v[220:221], off
	s_waitcnt vmcnt(8)
	s_waitcnt lgkmcnt(0)
	s_barrier
; #define PG8_STAGE(bufoff, gbase, voff) do { _Pragma("unroll") for (int _i = 0; _i < 2; ++_i) \
;     __builtin_amdgcn_global_load_lds((const unsigned*)((const char*)(gbase) + (voff)[_i]), (PG8_LAS unsigned*)(lds + (bufoff) + ldsw + _i * 8192), 16, 0, 0); } while (0)
; #define PG8_LDA(dst, b, h) do { _Pragma("unroll") for (int m = 0; m < 4; ++m) _Pragma("unroll") for (int k = 0; k < 2; ++k) dst[m][k] = *(const PG8_LAS bf16x8*)(lds + PG8_SA(b, h) + aoff + m * 2048 + k * 1024); } while (0)
; #define PG8_LDB(dst, b, h) do { _Pragma("unroll") for (int n = 0; n < 2; ++n) _Pragma("unroll") for (int k = 0; k < 2; ++k) dst[n][k] = *(const PG8_LAS bf16x8*)(lds + PG8_SB(b, h) + boff + n * 2048 + k * 1024); } while (0)
; #define PG8_MMA(ai, bj, At, Bt) do { __builtin_amdgcn_s_setprio(1); _Pragma("unroll") for (int m = 0; m < 4; ++m) _Pragma("unroll") for (int n = 0; n < 2; ++n) _Pragma("unroll") for (int k = 0; k < 2; ++k) \
;     acc[ai][bj][m][n] = __builtin_amdgcn_mfma_f32_16x16x32_bf16(Bt[n][k], At[m][k], acc[ai][bj][m][n], 0, 0, 0); __builtin_amdgcn_s_setprio(0); } while (0)
; #define PG8_WAIT_V(n) asm volatile("s_waitcnt vmcnt(" #n ")" ::: "memory")
; #define PG8_WAIT_L(n) asm volatile("s_waitcnt lgkmcnt(" #n ")" ::: "memory")
; #define PG8_BAR __builtin_amdgcn_s_barrier()
; #define PG8_SCHED __builtin_amdgcn_sched_barrier(0)
; template <class Epi>
; DEV void gemm_phase(PG8_LAS unsigned char* lds, const Gemm g, const StaticOrder& S, const Epi& E) {
;     ...
;       PG8_WAIT_V(8); PG8_WAIT_L(0); PG8_BAR; PG8_MMA(1, 0, At, B0); PG8_MMA(1, 1, At, B1); PG8_BAR; PG8_SCHED;
;       PG8_LDB(B0, 1, 0); PG8_LDB(B1, 1, 1); PG8_SCHED; PG8_LDA(At, 1, 0); PG8_STAGE(PG8_SA(0, 1), a2 + hstepA, voffA);
;       PG8_WAIT_V(8); PG8_WAIT_L(0); PG8_BAR; PG8_MMA(0, 0, At, B0); PG8_MMA(0, 1, At, B1); PG8_BAR; PG8_SCHED;
	s_waitcnt lgkmcnt(0)
	v_mfma_f32_16x16x32_bf16 v[62:65], v[130:133], v[162:165], v[62:65]
	v_mfma_f32_16x16x32_bf16 v[58:61], v[138:141], v[162:165], v[58:61]
	v_mfma_f32_16x16x32_bf16 v[54:57], v[130:133], v[170:173], v[54:57]
	v_mfma_f32_16x16x32_bf16 v[46:49], v[138:141], v[170:173], v[46:49]
	v_mfma_f32_16x16x32_bf16 v[28:31], v[130:133], v[194:197], v[28:31]
	v_mfma_f32_16x16x32_bf16 v[24:27], v[138:141], v[194:197], v[24:27]
	v_mfma_f32_16x16x32_bf16 v[16:19], v[130:133], v[206:209], v[16:19]
	v_mfma_f32_16x16x32_bf16 v[8:11], v[138:141], v[206:209], v[8:11]
	v_mfma_f32_16x16x32_bf16 v[62:65], v[134:137], v[166:169], v[62:65]
	v_mfma_f32_16x16x32_bf16 v[58:61], v[142:145], v[166:169], v[58:61]
	v_mfma_f32_16x16x32_bf16 v[54:57], v[134:137], v[174:177], v[54:57]
	v_mfma_f32_16x16x32_bf16 v[46:49], v[142:145], v[174:177], v[46:49]
	v_mfma_f32_16x16x32_bf16 v[28:31], v[134:137], v[202:205], v[28:31]
	v_mfma_f32_16x16x32_bf16 v[24:27], v[142:145], v[202:205], v[24:27]
	v_mfma_f32_16x16x32_bf16 v[16:19], v[134:137], v[210:213], v[16:19]
	v_mfma_f32_16x16x32_bf16 v[8:11], v[142:145], v[210:213], v[8:11]
	v_mfma_f32_16x16x32_bf16 v[50:53], v[146:149], v[162:165], v[50:53]
	v_mfma_f32_16x16x32_bf16 v[42:45], v[154:157], v[162:165], v[42:45]
	v_mfma_f32_16x16x32_bf16 v[36:39], v[146:149], v[170:173], v[36:39]
	v_mfma_f32_16x16x32_bf16 v[32:35], v[154:157], v[170:173], v[32:35]
	v_mfma_f32_16x16x32_bf16 v[20:23], v[146:149], v[194:197], v[20:23]
	v_mfma_f32_16x16x32_bf16 v[12:15], v[154:157], v[194:197], v[12:15]
	v_mfma_f32_16x16x32_bf16 v[4:7], v[146:149], v[206:209], v[4:7]
	v_mfma_f32_16x16x32_bf16 v[0:3], v[154:157], v[206:209], v[0:3]
	v_mfma_f32_16x16x32_bf16 v[50:53], v[150:153], v[166:169], v[50:53]
	v_mfma_f32_16x16x32_bf16 v[42:45], v[158:161], v[166:169], v[42:45]
	v_mfma_f32_16x16x32_bf16 v[36:39], v[150:153], v[174:177], v[36:39]
	v_mfma_f32_16x16x32_bf16 v[32:35], v[158:161], v[174:177], v[32:35]
	v_mfma_f32_16x16x32_bf16 v[20:23], v[150:153], v[202:205], v[20:23]
	v_mfma_f32_16x16x32_bf16 v[12:15], v[158:161], v[202:205], v[12:15]
	v_mfma_f32_16x16x32_bf16 v[4:7], v[150:153], v[210:213], v[4:7]
	v_mfma_f32_16x16x32_bf16 v[0:3], v[158:161], v[210:213], v[0:3]
	s_barrier
	v_or_b32_e32 v40, 0x18000, v224
	v_add_u32_e32 v134, 0x18400, v224
	ds_read_b128 v[130:133], v40
	ds_read_b128 v[134:137], v134
	v_add_u32_e32 v40, 0x18800, v224
	v_add_u32_e32 v142, 0x18c00, v224
	ds_read_b128 v[138:141], v40
	ds_read_b128 v[142:145], v142
	v_or_b32_e32 v40, 0x1c000, v224
	v_add_u32_e32 v150, 0x1c400, v224
	ds_read_b128 v[146:149], v40
	ds_read_b128 v[150:153], v150
	v_add_u32_e32 v40, 0x1c800, v224
	v_add_u32_e32 v158, 0x1cc00, v224
	ds_read_b128 v[154:157], v40
	ds_read_b128 v[158:161], v158
	s_add_u32 s42, s42, s22
	s_addc_u32 s43, s43, s23
	s_mov_b32 m0, s33
	v_lshl_add_u64 v[220:221], s[42:43], 0, v[182:183]
	ds_read_b128 v[162:165], v223 offset:32768
	ds_read_b128 v[166:169], v223 offset:33792
	ds_read_b128 v[170:173], v223 offset:34816
	ds_read_b128 v[174:177], v223 offset:35840
	ds_read_b128 v[194:197], v223 offset:36864
	ds_read_b128 v[202:205], v223 offset:37888
	ds_read_b128 v[206:209], v223 offset:38912
	ds_read_b128 v[210:213], v223 offset:39936
	global_load_lds_dwordx4 v[220:221], off
	v_lshl_add_u64 v[220:221], s[42:43], 0, v[178:179]
	s_mov_b32 m0, s30
	s_nop 0
	global_load_lds_dwordx4 v[220:221], off
	s_waitcnt vmcnt(8)
	s_waitcnt lgkmcnt(0)
	s_barrier
	s_waitcnt lgkmcnt(0)
	v_mfma_f32_16x16x32_bf16 v[126:129], v[130:133], v[162:165], v[126:129]
	v_mfma_f32_16x16x32_bf16 v[122:125], v[138:141], v[162:165], v[122:125]
	v_mfma_f32_16x16x32_bf16 v[118:121], v[130:133], v[170:173], v[118:121]
	v_mfma_f32_16x16x32_bf16 v[110:113], v[138:141], v[170:173], v[110:113]
	v_mfma_f32_16x16x32_bf16 v[94:97], v[130:133], v[194:197], v[94:97]
	v_mfma_f32_16x16x32_bf16 v[90:93], v[138:141], v[194:197], v[90:93]
	v_mfma_f32_16x16x32_bf16 v[86:89], v[130:133], v[206:209], v[86:89]
	v_mfma_f32_16x16x32_bf16 v[78:81], v[138:141], v[206:209], v[78:81]
	v_mfma_f32_16x16x32_bf16 v[126:129], v[134:137], v[166:169], v[126:129]
	v_mfma_f32_16x16x32_bf16 v[122:125], v[142:145], v[166:169], v[122:125]
	v_mfma_f32_16x16x32_bf16 v[118:121], v[134:137], v[174:177], v[118:121]
	v_mfma_f32_16x16x32_bf16 v[110:113], v[142:145], v[174:177], v[110:113]
	v_mfma_f32_16x16x32_bf16 v[94:97], v[134:137], v[202:205], v[94:97]
	v_mfma_f32_16x16x32_bf16 v[90:93], v[142:145], v[202:205], v[90:93]
	v_mfma_f32_16x16x32_bf16 v[86:89], v[134:137], v[210:213], v[86:89]
	v_mfma_f32_16x16x32_bf16 v[78:81], v[142:145], v[210:213], v[78:81]
	v_mfma_f32_16x16x32_bf16 v[114:117], v[146:149], v[162:165], v[114:117]
	v_mfma_f32_16x16x32_bf16 v[106:109], v[154:157], v[162:165], v[106:109]
	v_mfma_f32_16x16x32_bf16 v[102:105], v[146:149], v[170:173], v[102:105]
	v_mfma_f32_16x16x32_bf16 v[98:101], v[154:157], v[170:173], v[98:101]
	v_mfma_f32_16x16x32_bf16 v[82:85], v[146:149], v[194:197], v[82:85]
	v_mfma_f32_16x16x32_bf16 v[74:77], v[154:157], v[194:197], v[74:77]
	v_mfma_f32_16x16x32_bf16 v[70:73], v[146:149], v[206:209], v[70:73]
	v_mfma_f32_16x16x32_bf16 v[66:69], v[154:157], v[206:209], v[66:69]
	v_mfma_f32_16x16x32_bf16 v[114:117], v[150:153], v[166:169], v[114:117]
	v_mfma_f32_16x16x32_bf16 v[106:109], v[158:161], v[166:169], v[106:109]
	v_mfma_f32_16x16x32_bf16 v[102:105], v[150:153], v[174:177], v[102:105]
	v_mfma_f32_16x16x32_bf16 v[98:101], v[158:161], v[174:177], v[98:101]
	v_mfma_f32_16x16x32_bf16 v[82:85], v[150:153], v[202:205], v[82:85]
	v_mfma_f32_16x16x32_bf16 v[74:77], v[158:161], v[202:205], v[74:77]
	v_mfma_f32_16x16x32_bf16 v[70:73], v[150:153], v[210:213], v[70:73]
	v_mfma_f32_16x16x32_bf16 v[66:69], v[158:161], v[210:213], v[66:69]
	s_barrier
; #define PG8_STAGE(bufoff, gbase, voff) do { _Pragma("unroll") for (int _i = 0; _i < 2; ++_i) \
;     __builtin_amdgcn_global_load_lds((const unsigned*)((const char*)(gbase) + (voff)[_i]), (PG8_LAS unsigned*)(lds + (bufoff) + ldsw + _i * 8192), 16, 0, 0); } while (0)
; #define PG8_LDA(dst, b, h) do { _Pragma("unroll") for (int m = 0; m < 4; ++m) _Pragma("unroll") for (int k = 0; k < 2; ++k) dst[m][k] = *(const PG8_LAS bf16x8*)(lds + PG8_SA(b, h) + aoff + m * 2048 + k * 1024); } while (0)
; #define PG8_MMA(ai, bj, At, Bt) do { __builtin_amdgcn_s_setprio(1); _Pragma("unroll") for (int m = 0; m < 4; ++m) _Pragma("unroll") for (int n = 0; n < 2; ++n) _Pragma("unroll") for (int k = 0; k < 2; ++k) \
;     acc[ai][bj][m][n] = __builtin_amdgcn_mfma_f32_16x16x32_bf16(Bt[n][k], At[m][k], acc[ai][bj][m][n], 0, 0, 0); __builtin_amdgcn_s_setprio(0); } while (0)
; #define PG8_WAIT_V(n) asm volatile("s_waitcnt vmcnt(" #n ")" ::: "memory")
; #define PG8_WAIT_L(n) asm volatile("s_waitcnt lgkmcnt(" #n ")" ::: "memory")
; #define PG8_BAR __builtin_amdgcn_s_barrier()
; #define PG8_SCHED __builtin_amdgcn_sched_barrier(0)
; template <class Epi>
; DEV void gemm_phase(PG8_LAS unsigned char* lds, const Gemm g, const StaticOrder& S, const Epi& E) {
;     ...
;       PG8_LDA(At, 1, 1); PG8_STAGE(PG8_SB(1, 0), b3, voffB); PG8_STAGE(PG8_SB(1, 1), b3 + hstepB, voffB); PG8_STAGE(PG8_SA(1, 0), a3, voffA);
;       PG8_WAIT_V(8); PG8_WAIT_L(0); PG8_BAR; PG8_MMA(1, 0, At, B0); PG8_MMA(1, 1, At, B1); PG8_BAR; PG8_SCHED;
;     }
	s_mov_b32 m0, s0
	v_lshl_add_u64 v[198:199], v[198:199], 0, s[96:97]
	ds_read_b128 v[162:165], v223 offset:49152
	ds_read_b128 v[166:169], v223 offset:50176
	ds_read_b128 v[170:173], v223 offset:51200
	ds_read_b128 v[174:177], v223 offset:52224
	ds_read_b128 v[194:197], v223 offset:53248
	ds_read_b128 v[202:205], v223 offset:54272
	ds_read_b128 v[206:209], v223 offset:55296
	ds_read_b128 v[210:213], v223 offset:56320
	global_load_lds_dwordx4 v[198:199], off
	v_lshl_add_u64 v[198:199], v[214:215], 0, s[96:97]
	s_mov_b32 m0, s1
	s_nop 0
	global_load_lds_dwordx4 v[198:199], off
	v_lshl_add_u64 v[198:199], v[216:217], 0, s[96:97]
	s_mov_b32 m0, s76
	s_nop 0
	global_load_lds_dwordx4 v[198:199], off
	v_lshl_add_u64 v[198:199], v[218:219], 0, s[96:97]
	s_mov_b32 m0, s77
	s_nop 0
	global_load_lds_dwordx4 v[198:199], off
	v_lshl_add_u64 v[198:199], s[46:47], 0, v[182:183]
	s_mov_b32 m0, s16
	s_nop 0
	global_load_lds_dwordx4 v[198:199], off
	v_lshl_add_u64 v[198:199], s[46:47], 0, v[178:179]
	s_mov_b32 m0, s17
	s_nop 0
	global_load_lds_dwordx4 v[198:199], off
	s_waitcnt vmcnt(8)
	s_waitcnt lgkmcnt(0)
	s_barrier
	s_waitcnt lgkmcnt(0)
	v_mfma_f32_16x16x32_bf16 v[62:65], v[130:133], v[162:165], v[62:65]
	v_mfma_f32_16x16x32_bf16 v[58:61], v[138:141], v[162:165], v[58:61]
	v_mfma_f32_16x16x32_bf16 v[54:57], v[130:133], v[170:173], v[54:57]
	v_mfma_f32_16x16x32_bf16 v[46:49], v[138:141], v[170:173], v[46:49]
	v_mfma_f32_16x16x32_bf16 v[28:31], v[130:133], v[194:197], v[28:31]
	v_mfma_f32_16x16x32_bf16 v[24:27], v[138:141], v[194:197], v[24:27]
	v_mfma_f32_16x16x32_bf16 v[16:19], v[130:133], v[206:209], v[16:19]
	v_mfma_f32_16x16x32_bf16 v[8:11], v[138:141], v[206:209], v[8:11]
	v_mfma_f32_16x16x32_bf16 v[62:65], v[134:137], v[166:169], v[62:65]
	v_mfma_f32_16x16x32_bf16 v[58:61], v[142:145], v[166:169], v[58:61]
	v_mfma_f32_16x16x32_bf16 v[54:57], v[134:137], v[174:177], v[54:57]
	v_mfma_f32_16x16x32_bf16 v[46:49], v[142:145], v[174:177], v[46:49]
	v_mfma_f32_16x16x32_bf16 v[28:31], v[134:137], v[202:205], v[28:31]
	v_mfma_f32_16x16x32_bf16 v[24:27], v[142:145], v[202:205], v[24:27]
	v_mfma_f32_16x16x32_bf16 v[16:19], v[134:137], v[210:213], v[16:19]
	v_mfma_f32_16x16x32_bf16 v[8:11], v[142:145], v[210:213], v[8:11]
	v_mfma_f32_16x16x32_bf16 v[50:53], v[146:149], v[162:165], v[50:53]
	v_mfma_f32_16x16x32_bf16 v[42:45], v[154:157], v[162:165], v[42:45]
	v_mfma_f32_16x16x32_bf16 v[36:39], v[146:149], v[170:173], v[36:39]
	v_mfma_f32_16x16x32_bf16 v[32:35], v[154:157], v[170:173], v[32:35]
	v_mfma_f32_16x16x32_bf16 v[20:23], v[146:149], v[194:197], v[20:23]
	v_mfma_f32_16x16x32_bf16 v[12:15], v[154:157], v[194:197], v[12:15]
	v_mfma_f32_16x16x32_bf16 v[4:7], v[146:149], v[206:209], v[4:7]
	v_mfma_f32_16x16x32_bf16 v[0:3], v[154:157], v[206:209], v[0:3]
	v_mfma_f32_16x16x32_bf16 v[50:53], v[150:153], v[166:169], v[50:53]
	v_mfma_f32_16x16x32_bf16 v[42:45], v[158:161], v[166:169], v[42:45]
	v_mfma_f32_16x16x32_bf16 v[36:39], v[150:153], v[174:177], v[36:39]
	v_mfma_f32_16x16x32_bf16 v[32:35], v[158:161], v[174:177], v[32:35]
	v_mfma_f32_16x16x32_bf16 v[20:23], v[150:153], v[202:205], v[20:23]
	v_mfma_f32_16x16x32_bf16 v[12:15], v[158:161], v[202:205], v[12:15]
	v_mfma_f32_16x16x32_bf16 v[4:7], v[150:153], v[210:213], v[4:7]
	v_mfma_f32_16x16x32_bf16 v[0:3], v[158:161], v[210:213], v[0:3]
	s_barrier
	s_add_u32 s10, s10, 0x100
	s_addc_u32 s11, s11, 0
	s_add_u32 s44, s44, s6
	s_addc_u32 s45, s45, s7
	s_cmp_ge_u32 s50, s36
	s_cbranch_scc1 .LBB0_559
